# Odd layers: short gated conv executed by idle waves 5-7 inside the S5 chunk loop (loads issued one chunk ahead), separate conv loop removed
# speedup vs baseline: 1.0576x; 1.0017x over previous
.LBB0_1089:
	s_and_b32 s42, s44, 31
	s_lshl_b32 s42, s42, 5
	s_mov_b32 s43, s3
	v_lshl_add_u64 v[114:115], s[40:41], 0, v[66:67]
	v_mov_b32_e32 v66, v67
	v_lshl_add_u64 v[112:113], v[84:85], 0, s[42:43]
	v_cndmask_b32_e64 v109, v16, v138, s[6:7]
	v_cndmask_b32_e64 v144, v17, v139, s[6:7]
	v_cndmask_b32_e64 v145, v18, v140, s[6:7]
	v_cndmask_b32_e64 v146, v19, v141, s[6:7]
	v_lshl_add_u64 v[116:117], v[82:83], 0, s[36:37]
	v_lshl_add_u64 v[110:111], v[86:87], 0, s[2:3]
	v_lshl_add_u64 v[118:119], v[78:79], 0, s[2:3]
	v_xor_b32_e32 v62, 0x80000000, v63
	v_mov_b32_e32 v61, v60
	v_lshl_add_u64 v[120:121], v[94:95], 0, s[38:39]
	s_mov_b32 s40, 0
	s_movk_i32 s2, 0xffc0
	v_mov_b64_e32 v[122:123], v[66:67]
	s_waitcnt lgkmcnt(0)
	v_lshrrev_b32_e32 v204, 6, v206
	v_and_b32_e32 v205, 63, v206
	v_readfirstlane_b32 s72, v204
	s_load_dwordx2 s[58:59], s[0:1], 0xf0
	s_load_dwordx2 s[70:71], s[0:1], 0xd8
	v_lshlrev_b32_e32 v204, 5, v205
	v_lshlrev_b32_e32 v205, 4, v205
	s_mov_b32 s54, 0
	s_mov_b32 s55, 0
	s_waitcnt lgkmcnt(0)
	s_add_u32 s60, s58, 0xc000000
	s_addc_u32 s61, s59, 0
	s_add_u32 s58, s58, 0x10000000
	s_addc_u32 s59, s59, 0
	global_load_dwordx4 v[208:211], v204, s[70:71]
	global_load_dwordx4 v[212:215], v204, s[70:71] offset:16
	s_add_u32 s70, s70, 0x800
	s_addc_u32 s71, s71, 0
	global_load_dwordx4 v[216:219], v204, s[70:71]
	global_load_dwordx4 v[220:223], v204, s[70:71] offset:16
	s_add_u32 s70, s70, 0x800
	s_addc_u32 s71, s71, 0
	global_load_dwordx4 v[224:227], v204, s[70:71]
	global_load_dwordx4 v[228:231], v204, s[70:71] offset:16
	s_waitcnt vmcnt(0)
	s_barrier
	s_branch .LBB0_1092

.LBB0_1092:
	s_and_b64 vcc, exec, s[28:29]
	s_cbranch_vccz .LBB0_1107
	s_mov_b32 s100, 0
	s_cmp_lt_u32 s72, 5
	s_cbranch_scc1 .Lcv_done_0
	s_cmp_eq_u32 s54, 0
	s_cbranch_scc1 .Lcv_noprev_0
	s_and_b32 s70, s56, 0xfff
	v_lshlrev_b32_e32 v200, 16, v232
	v_and_b32_e32 v201, 0xffff0000, v232
	v_lshlrev_b32_e32 v202, 16, v236
	v_and_b32_e32 v203, 0xffff0000, v236
	v_pk_mul_f32 v[200:201], v[208:209], v[200:201]
	v_pk_mul_f32 v[192:193], v[200:201], v[202:203]
	v_lshlrev_b32_e32 v200, 16, v233
	v_and_b32_e32 v201, 0xffff0000, v233
	v_lshlrev_b32_e32 v202, 16, v237
	v_and_b32_e32 v203, 0xffff0000, v237
	v_pk_mul_f32 v[200:201], v[210:211], v[200:201]
	v_pk_mul_f32 v[194:195], v[200:201], v[202:203]
	v_lshlrev_b32_e32 v200, 16, v234
	v_and_b32_e32 v201, 0xffff0000, v234
	v_lshlrev_b32_e32 v202, 16, v238
	v_and_b32_e32 v203, 0xffff0000, v238
	v_pk_mul_f32 v[200:201], v[212:213], v[200:201]
	v_pk_mul_f32 v[196:197], v[200:201], v[202:203]
	v_lshlrev_b32_e32 v200, 16, v235
	v_and_b32_e32 v201, 0xffff0000, v235
	v_lshlrev_b32_e32 v202, 16, v239
	v_and_b32_e32 v203, 0xffff0000, v239
	v_pk_mul_f32 v[200:201], v[214:215], v[200:201]
	v_pk_mul_f32 v[198:199], v[200:201], v[202:203]
	s_cmp_lt_u32 s70, 1
	s_cbranch_scc1 .Lcv_taps_done_0
	v_lshlrev_b32_e32 v200, 16, v240
	v_and_b32_e32 v201, 0xffff0000, v240
	v_lshlrev_b32_e32 v202, 16, v244
	v_and_b32_e32 v203, 0xffff0000, v244
	v_pk_mul_f32 v[200:201], v[216:217], v[200:201]
	v_pk_fma_f32 v[192:193], v[200:201], v[202:203], v[192:193]
	v_lshlrev_b32_e32 v200, 16, v241
	v_and_b32_e32 v201, 0xffff0000, v241
	v_lshlrev_b32_e32 v202, 16, v245
	v_and_b32_e32 v203, 0xffff0000, v245
	v_pk_mul_f32 v[200:201], v[218:219], v[200:201]
	v_pk_fma_f32 v[194:195], v[200:201], v[202:203], v[194:195]
	v_lshlrev_b32_e32 v200, 16, v242
	v_and_b32_e32 v201, 0xffff0000, v242
	v_lshlrev_b32_e32 v202, 16, v246
	v_and_b32_e32 v203, 0xffff0000, v246
	v_pk_mul_f32 v[200:201], v[220:221], v[200:201]
	v_pk_fma_f32 v[196:197], v[200:201], v[202:203], v[196:197]
	v_lshlrev_b32_e32 v200, 16, v243
	v_and_b32_e32 v201, 0xffff0000, v243
	v_lshlrev_b32_e32 v202, 16, v247
	v_and_b32_e32 v203, 0xffff0000, v247
	v_pk_mul_f32 v[200:201], v[222:223], v[200:201]
	v_pk_fma_f32 v[198:199], v[200:201], v[202:203], v[198:199]
	s_cmp_lt_u32 s70, 2
	s_cbranch_scc1 .Lcv_taps_done_0
	v_lshlrev_b32_e32 v200, 16, v248
	v_and_b32_e32 v201, 0xffff0000, v248
	v_lshlrev_b32_e32 v202, 16, v184
	v_and_b32_e32 v203, 0xffff0000, v184
	v_pk_mul_f32 v[200:201], v[224:225], v[200:201]
	v_pk_fma_f32 v[192:193], v[200:201], v[202:203], v[192:193]
	v_lshlrev_b32_e32 v200, 16, v249
	v_and_b32_e32 v201, 0xffff0000, v249
	v_lshlrev_b32_e32 v202, 16, v185
	v_and_b32_e32 v203, 0xffff0000, v185
	v_pk_mul_f32 v[200:201], v[226:227], v[200:201]
	v_pk_fma_f32 v[194:195], v[200:201], v[202:203], v[194:195]
	v_lshlrev_b32_e32 v200, 16, v250
	v_and_b32_e32 v201, 0xffff0000, v250
	v_lshlrev_b32_e32 v202, 16, v186
	v_and_b32_e32 v203, 0xffff0000, v186
	v_pk_mul_f32 v[200:201], v[228:229], v[200:201]
	v_pk_fma_f32 v[196:197], v[200:201], v[202:203], v[196:197]
	v_lshlrev_b32_e32 v200, 16, v251
	v_and_b32_e32 v201, 0xffff0000, v251
	v_lshlrev_b32_e32 v202, 16, v187
	v_and_b32_e32 v203, 0xffff0000, v187
	v_pk_mul_f32 v[200:201], v[230:231], v[200:201]
	v_pk_fma_f32 v[198:199], v[200:201], v[202:203], v[198:199]
.Lcv_taps_done_0:
	v_lshlrev_b32_e32 v200, 16, v188
	v_and_b32_e32 v201, 0xffff0000, v188
	v_pk_mul_f32 v[192:193], v[192:193], v[200:201]
	v_lshlrev_b32_e32 v200, 16, v189
	v_and_b32_e32 v201, 0xffff0000, v189
	v_pk_mul_f32 v[194:195], v[194:195], v[200:201]
	v_lshlrev_b32_e32 v200, 16, v190
	v_and_b32_e32 v201, 0xffff0000, v190
	v_pk_mul_f32 v[196:197], v[196:197], v[200:201]
	v_lshlrev_b32_e32 v200, 16, v191
	v_and_b32_e32 v201, 0xffff0000, v191
	v_pk_mul_f32 v[198:199], v[198:199], v[200:201]
	v_cvt_pk_bf16_f32 v232, v192, v193
	v_cvt_pk_bf16_f32 v233, v194, v195
	v_cvt_pk_bf16_f32 v234, v196, v197
	v_cvt_pk_bf16_f32 v235, v198, v199
	global_store_dwordx4 v205, v[232:235], s[68:69] offset:1024
.Lcv_noprev_0:
	s_mov_b32 s54, 0
	s_cmp_ge_u32 s55, 43
	s_cbranch_scc1 .Lcv_done_0
	s_mul_i32 s57, s55, 0x300
	s_mul_i32 s70, s96, 3
	s_add_u32 s57, s57, s70
	s_add_u32 s57, s57, s72
	s_sub_u32 s57, s57, 5
	s_cmp_ge_u32 s57, 0x8000
	s_cbranch_scc1 .Lcv_noissue_0
	s_lshl_b32 s70, s57, 12
	s_add_u32 s62, s58, s70
	s_addc_u32 s63, s59, 0
	s_sub_u32 s64, s62, 0x1000
	s_subb_u32 s65, s63, 0
	s_sub_u32 s66, s62, 0x2000
	s_subb_u32 s67, s63, 0
	s_lshl_b32 s70, s57, 11
	s_add_u32 s68, s60, s70
	s_addc_u32 s69, s61, 0
	global_load_dwordx4 v[232:235], v205, s[62:63] offset:2048
	global_load_dwordx4 v[236:239], v205, s[62:63] offset:3072
	global_load_dwordx4 v[240:243], v205, s[64:65] offset:2048
	global_load_dwordx4 v[244:247], v205, s[64:65] offset:3072
	global_load_dwordx4 v[248:251], v205, s[66:67] offset:2048
	global_load_dwordx4 v[184:187], v205, s[66:67] offset:3072
	global_load_dwordx4 v[188:191], v205, s[62:63] offset:1024
	s_mov_b32 s56, s57
	s_mov_b32 s54, 1
	s_add_u32 s55, s55, 1
	s_branch .Lcv_done_0
.Lcv_noissue_0:
	s_mov_b32 s54, 0
	s_mov_b32 s55, 43
.Lcv_done_0:
	v_mov_b64_e32 v[0:1], v[56:57]
	v_mov_b64_e32 v[4:5], v[52:53]
	s_cmpk_eq_i32 s2, 0xf80
	v_mov_b64_e32 v[2:3], v[58:59]
	v_mov_b64_e32 v[6:7], v[54:55]
	s_cbranch_scc1 .LBB0_1103
	s_cmp_lt_i32 s45, 1
	v_mov_b32_e32 v0, v97
	v_mov_b32_e32 v1, v99
	v_mov_b32_e32 v2, v101
	v_mov_b32_e32 v3, v103
	s_cbranch_scc1 .LBB0_1099
	s_cmp_lg_u32 s45, 1
	s_mov_b64 s[38:39], -1
	s_cbranch_scc0 .LBB0_1097
	s_mov_b64 s[38:39], 0

.LBB0_1111:
	s_mov_b64 s[4:5], s[0:1]
	s_load_dwordx2 s[2:3], s[4:5], 0xf0
	v_mov_b32_e32 v0, v206
	s_mov_b32 s12, s96
	s_mov_b32 s6, 0
	v_lshl_add_u32 v16, s12, 9, v0
	v_cmp_gt_i32_e32 vcc, s6, v16
	s_and_saveexec_b64 s[6:7], vcc
	s_cbranch_execz .LBB0_1118
	s_load_dwordx2 s[8:9], s[4:5], 0xd8
	s_waitcnt lgkmcnt(0)
	s_add_u32 s10, s2, 0x10000000
	v_lshlrev_b32_e32 v0, 3, v0
	s_addc_u32 s11, s3, 0
	v_lshl_add_u32 v17, s12, 12, v0
	s_lshl_b32 s18, s33, 12
	s_mov_b64 s[12:13], 0
	v_mov_b32_e32 v1, 0
	s_mov_b64 s[14:15], 0x1000
	s_movk_i32 s19, 0x1000
	s_mov_b32 s20, 0x1fffff
	v_mov_b32_e32 v22, v16
	s_branch .LBB0_1114

.LBB0_2569:
	s_and_b32 s2, s44, 31
	s_lshl_b32 s2, s2, 5
	v_lshl_add_u64 v[112:113], v[84:85], 0, s[2:3]
	v_lshl_add_u64 v[114:115], s[40:41], 0, v[66:67]
	s_lshl_b32 s2, s53, 1
	v_mov_b32_e32 v66, v67
	v_cndmask_b32_e64 v109, v16, v138, s[6:7]
	v_cndmask_b32_e64 v144, v17, v139, s[6:7]
	v_cndmask_b32_e64 v145, v18, v140, s[6:7]
	v_cndmask_b32_e64 v146, v19, v141, s[6:7]
	v_lshl_add_u64 v[116:117], v[82:83], 0, s[36:37]
	v_lshl_add_u64 v[110:111], v[86:87], 0, s[2:3]
	v_lshl_add_u64 v[118:119], v[78:79], 0, s[2:3]
	v_xor_b32_e32 v62, 0x80000000, v63
	v_mov_b32_e32 v61, v60
	v_lshl_add_u64 v[120:121], v[94:95], 0, s[38:39]
	s_mov_b32 s40, 0
	s_movk_i32 s2, 0xffc0
	v_mov_b64_e32 v[122:123], v[66:67]
	s_waitcnt lgkmcnt(0)
	v_lshrrev_b32_e32 v204, 6, v206
	v_and_b32_e32 v205, 63, v206
	v_readfirstlane_b32 s72, v204
	s_load_dwordx2 s[58:59], s[0:1], 0xf0
	s_load_dwordx2 s[70:71], s[0:1], 0xd8
	v_lshlrev_b32_e32 v204, 5, v205
	v_lshlrev_b32_e32 v205, 4, v205
	s_mov_b32 s54, 0
	s_mov_b32 s55, 0
	s_waitcnt lgkmcnt(0)
	s_add_u32 s60, s58, 0xc000000
	s_addc_u32 s61, s59, 0
	s_add_u32 s58, s58, 0x10000000
	s_addc_u32 s59, s59, 0
	s_add_u32 s70, s70, 0x1800
	s_addc_u32 s71, s71, 0
	global_load_dwordx4 v[208:211], v204, s[70:71]
	global_load_dwordx4 v[212:215], v204, s[70:71] offset:16
	s_add_u32 s70, s70, 0x800
	s_addc_u32 s71, s71, 0
	global_load_dwordx4 v[216:219], v204, s[70:71]
	global_load_dwordx4 v[220:223], v204, s[70:71] offset:16
	s_add_u32 s70, s70, 0x800
	s_addc_u32 s71, s71, 0
	global_load_dwordx4 v[224:227], v204, s[70:71]
	global_load_dwordx4 v[228:231], v204, s[70:71] offset:16
	s_waitcnt vmcnt(0)
	s_barrier
	s_branch .LBB0_2572

.Lcv_noprev_1:
	s_mov_b32 s54, 0
	s_cmp_ge_u32 s55, 43
	s_cbranch_scc1 .Lcv_done_1
	s_mul_i32 s57, s55, 0x300
	s_mul_i32 s70, s95, 3
	s_add_u32 s57, s57, s70
	s_add_u32 s57, s57, s72
	s_sub_u32 s57, s57, 5
	s_cmp_ge_u32 s57, 0x8000
	s_cbranch_scc1 .Lcv_noissue_1
	s_lshl_b32 s70, s57, 12
	s_add_u32 s62, s58, s70
	s_addc_u32 s63, s59, 0
	s_sub_u32 s64, s62, 0x1000
	s_subb_u32 s65, s63, 0
	s_sub_u32 s66, s62, 0x2000
	s_subb_u32 s67, s63, 0
	s_lshl_b32 s70, s57, 11
	s_add_u32 s68, s60, s70
	s_addc_u32 s69, s61, 0
	global_load_dwordx4 v[232:235], v205, s[62:63] offset:2048
	global_load_dwordx4 v[236:239], v205, s[62:63] offset:3072
	global_load_dwordx4 v[240:243], v205, s[64:65] offset:2048
	global_load_dwordx4 v[244:247], v205, s[64:65] offset:3072
	global_load_dwordx4 v[248:251], v205, s[66:67] offset:2048
	global_load_dwordx4 v[184:187], v205, s[66:67] offset:3072
	global_load_dwordx4 v[188:191], v205, s[62:63] offset:1024
	s_mov_b32 s56, s57
	s_mov_b32 s54, 1
	s_add_u32 s55, s55, 1
	s_branch .Lcv_done_1

.LBB0_2591:
	s_mov_b64 s[4:5], s[0:1]
	s_load_dwordx2 s[2:3], s[4:5], 0xf0
	v_mov_b32_e32 v0, v206
	s_mov_b32 s10, s95
	s_mov_b32 s6, 0
	v_lshl_add_u32 v16, s10, 9, v0
	v_cmp_gt_i32_e32 vcc, s6, v16
	s_and_saveexec_b64 s[6:7], vcc
	s_cbranch_execz .LBB0_2598
	s_load_dwordx2 s[12:13], s[4:5], 0xd8
	v_lshlrev_b32_e32 v0, 3, v0
	v_lshl_add_u32 v17, s10, 12, v0
	s_mov_b64 s[8:9], 0
	v_mov_b32_e32 v1, 0
	s_waitcnt lgkmcnt(0)
	s_add_u32 s10, s12, 0x1800
	s_addc_u32 s11, s13, 0
	s_add_u32 s12, s2, 0x10000000
	s_addc_u32 s13, s3, 0
	s_lshl_b32 s18, s33, 12
	s_mov_b64 s[14:15], 0x1000
	s_movk_i32 s19, 0x1000
	s_mov_b32 s20, 0x1fffff
	v_mov_b32_e32 v22, v16
	s_branch .LBB0_2594
